# v38: v37 + static priority raise for waves 0-3 in the two attention phases
# baseline (speedup 1.0000x reference)
.Lprio6:
.LBB0_1040:
	s_cmp_gt_i32 s58, 6
	s_cselect_b64 s[2:3], -1, 0
	s_cmp_lt_i32 s59, 7
	s_cselect_b64 s[4:5], -1, 0
	s_or_b64 s[2:3], s[2:3], s[4:5]
	s_and_b64 vcc, exec, s[2:3]
	s_cbranch_vccnz .LBB0_1160
	s_waitcnt vmcnt(0)
	v_mov_b32_e32 v6, 0
	ds_read_b64 v[8:9], v6 offset:416
	ds_read_b128 v[2:5], v6 offset:256
	s_mov_b64 s[2:3], 20
	v_mov_b32_e32 v1, 0
	v_mov_b32_e32 v7, 0
	s_waitcnt lgkmcnt(1)
	v_readfirstlane_b32 s34, v8
	v_readfirstlane_b32 s35, v9

.LBB0_1106:
	s_cmp_lt_i32 s59, 8
	s_barrier
	s_cbranch_scc1 .LBB0_1160
	s_waitcnt vmcnt(0)
	s_setprio 0
	s_barrier
	s_and_saveexec_b64 s[2:3], s[0:1]
	s_cbranch_execz .LBB0_1159
	s_waitcnt vmcnt(0) lgkmcnt(0)
	v_mov_b32_e32 v241, 0
	v_lshlrev_b32_e64 v254, 8, s31
	v_mov_b32_e32 v247, 1
	v_add_u32_e32 v246, 0x1400, v254
	global_atomic_add v248, v246, v247, s[60:61] sc0

.Lprio14:
.LBB0_2756:
	s_cmp_gt_i32 s58, 16
	s_cselect_b64 s[2:3], -1, 0
	s_cmp_lt_i32 s59, 17
	s_cselect_b64 s[4:5], -1, 0
	s_or_b64 s[2:3], s[2:3], s[4:5]
	s_and_b64 vcc, exec, s[2:3]
	s_cbranch_vccnz .LBB0_2898
	s_waitcnt vmcnt(0)
	s_mov_b32 s101, 0
	v_mov_b32_e32 v27, 0
	s_abs_i32 s9, s56
	ds_read_b64 v[4:5], v27 offset:416
	ds_read_b64 v[2:3], v27 offset:336
	v_cvt_f32_u32_e32 v6, s9
	s_sub_i32 s11, 0, s9
	s_add_i32 s10, s56, s30
	s_waitcnt lgkmcnt(1)
	v_readfirstlane_b32 s6, v4
	v_rcp_iflag_f32_e32 v4, v6
	s_abs_i32 s5, s10
	s_lshl_b32 s4, s68, 4
	s_and_b32 s8, s4, 0x3fffffc0
	v_mul_f32_e32 v4, 0x4f7ffffe, v4
	v_cvt_u32_f32_e32 v4, v4
	s_ashr_i32 s4, s10, 31
	v_and_b32_e32 v1, 15, v0
	v_readfirstlane_b32 s7, v5
	v_readfirstlane_b32 s12, v4
	s_mul_i32 s11, s11, s12
	s_mul_hi_u32 s11, s12, s11
	s_add_i32 s11, s12, s11
	s_mul_hi_u32 s12, s5, s11
	s_mul_i32 s12, s12, s9
	s_sub_i32 s5, s5, s12
	s_sub_i32 s12, s5, s9
	s_cmp_ge_u32 s5, s9
	s_cselect_b32 s5, s12, s5
	s_sub_i32 s12, s5, s9
	s_cmp_ge_u32 s5, s9
	s_cselect_b32 s5, s12, s5
	s_xor_b32 s5, s5, s4
	s_sub_i32 s12, s5, s4
	s_waitcnt lgkmcnt(0)
	v_readfirstlane_b32 s2, v2
	v_readfirstlane_b32 s3, v3
	s_cmpk_gt_i32 s12, 0xbf
	v_or_b32_e32 v42, s8, v1
	s_cbranch_scc1 .LBB0_2761
	s_add_u32 s13, s6, 0xe128000
	s_addc_u32 s14, s7, 0
	s_add_u32 s4, s6, 0x4928000
	v_and_b32_e32 v2, 48, v0
	v_lshlrev_b32_e32 v5, 6, v42
	s_movk_i32 s18, 0x3c0
	s_addc_u32 s5, s7, 0
	v_lshl_or_b32 v3, v1, 6, v2
	v_and_or_b32 v5, v5, s18, v2
	v_lshlrev_b32_e32 v2, 2, v42
	s_add_u32 s15, s6, 0x30c8000
	v_and_b32_e32 v6, 32, v2
	v_lshlrev_b32_e32 v2, 4, v0
	s_addc_u32 s16, s7, 0
	v_lshlrev_b32_e32 v4, 2, v0
	s_lshl_b32 s17, s68, 5
	v_bitop3_b32 v2, v0, v2, 32 bitop3:0x6c
	v_lshrrev_b32_e32 v9, 3, v0
	v_lshrrev_b32_e32 v11, 1, v0
	v_and_b32_e32 v4, 32, v4
	s_and_b32 s17, s17, 0x60
	s_lshl_b32 s19, s68, 10
	v_lshrrev_b32_e32 v2, 1, v2
	v_bfe_u32 v8, v0, 2, 4
	v_or_b32_e32 v10, 64, v9
	s_movk_i32 s18, 0x70
	v_and_b32_e32 v11, 32, v11
	s_lshl_b32 s23, s17, 7
	s_lshl_b32 s24, s8, 7
	v_lshrrev_b32_e32 v7, 2, v0
	v_and_or_b32 v10, v10, s18, v8
	v_and_or_b32 v2, v2, 24, v11
	v_and_or_b32 v8, v9, 48, v8
	v_xad_u32 v5, v5, v6, 0
	v_xad_u32 v3, v3, v4, 0
	s_add_i32 s22, s19, 0
	v_lshlrev_b32_e32 v26, 8, v8
	v_lshlrev_b32_e32 v28, 8, v10
	v_mov_b32_e32 v29, v27
	v_lshlrev_b32_e32 v30, 7, v8
	v_mov_b32_e32 v31, v27
	v_lshlrev_b32_e32 v32, 7, v10
	v_mov_b32_e32 v33, v27
	v_and_or_b32 v43, v7, 12, s17
	v_add_u32_e32 v44, s8, v1
	s_lshl_b32 s17, s12, 7
	s_lshl_b32 s18, s56, 7
	v_lshlrev_b32_e32 v34, 1, v2
	v_mov_b32_e32 v35, v27
	s_add_i32 s19, s22, 0x400
	s_add_i32 s20, s22, 0x2400
	s_add_i32 s21, s22, 0x4400
	s_addk_i32 s22, 0x6400
	v_add_u32_e32 v45, s24, v5
	v_add_u32_e32 v46, s23, v3

.LBB0_2844:
	s_cmp_lt_i32 s59, 18
	s_barrier
	s_cbranch_scc1 .LBB0_2898
	s_waitcnt vmcnt(0)
	s_setprio 0
	s_barrier
	s_and_saveexec_b64 s[2:3], s[0:1]
	s_cbranch_execz .LBB0_2897
	s_waitcnt vmcnt(0) lgkmcnt(0)
	v_mov_b32_e32 v241, 0
	v_lshlrev_b32_e64 v254, 8, s31
	v_mov_b32_e32 v247, 1
	v_add_u32_e32 v246, 0x1400, v254
	global_atomic_add v248, v246, v247, s[60:61] sc0
